# attention: scores and probabilities kept in the MFMA result registers (no copies), packed f32 subtract and sum, on top of pipelined PV
# speedup vs baseline: 1.0123x; 1.0019x over previous
; DI u32x4 pack8(const float* f) { u32x4 w; w.x = pk2(f[0], f[1]); w.y = pk2(f[2], f[3]); w.z = pk2(f[4], f[5]); w.w = pk2(f[6], f[7]); return w; }
; DI void attn_item(const Params& p, const Ctx& c, int l, int S, int tokbase, int qb, int kvh) {
;     ...
;         mx = fmaxf(mx, __shfl_xor(mx, 16)); mx = fmaxf(mx, __shfl_xor(mx, 32));
;         float sum = 0.f;
; #pragma unroll
;         for (int t = 0; t < 17; ++t)
; #pragma unroll
;             for (int r = 0; r < 4; ++r) { const float pv = __builtin_amdgcn_exp2f(s[t][r] - mx); s[t][r] = pv; sum += pv; }
;         sum += __shfl_xor(sum, 16); sum += __shfl_xor(sum, 32);
;         sum += __builtin_amdgcn_exp2f(sink - mx);
;         f32x4 o[4];
; #pragma unroll
;         for (int dt = 0; dt < 4; ++dt) o[dt] = (f32x4){0.f, 0.f, 0.f, 0.f};
; #pragma unroll
;         for (int u = 0; u < 9; ++u) {
;             float g[8];
; #pragma unroll
;             for (int r = 0; r < 4; ++r) { g[r] = s[2 * u][r]; g[4 + r] = (2 * u + 1 < 17) ? s[(2 * u + 1 < 17) ? 2 * u + 1 : 0][r] : 0.f; }
;             const bf16x8 bfr = __builtin_bit_cast(bf16x8, pack8(g));
.LBB0_316:
	ds_bpermute_b32 v216, v104, v188
	v_max_f32_e32 v217, v188, v188
	v_add_u32_e32 v108, 0x900, v108
	v_add_u32_e32 v102, 0x100, v102
	s_waitcnt lgkmcnt(0)
	v_max_f32_e32 v216, v216, v216
	v_max_f32_e32 v216, v217, v216
	ds_bpermute_b32 v217, v105, v216
	s_waitcnt lgkmcnt(0)
	v_max_f32_e32 v217, v217, v217
	v_max_f32_e32 v218, v216, v217
	s_nop 0
	v_pk_add_f32 v[26:27], v[26:27], v[218:219] op_sel_hi:[1,0] neg_lo:[0,1] neg_hi:[0,1]
	v_pk_add_f32 v[28:29], v[28:29], v[218:219] op_sel_hi:[1,0] neg_lo:[0,1] neg_hi:[0,1]
	v_pk_add_f32 v[30:31], v[30:31], v[218:219] op_sel_hi:[1,0] neg_lo:[0,1] neg_hi:[0,1]
	v_pk_add_f32 v[32:33], v[32:33], v[218:219] op_sel_hi:[1,0] neg_lo:[0,1] neg_hi:[0,1]
	v_pk_add_f32 v[34:35], v[34:35], v[218:219] op_sel_hi:[1,0] neg_lo:[0,1] neg_hi:[0,1]
	v_pk_add_f32 v[36:37], v[36:37], v[218:219] op_sel_hi:[1,0] neg_lo:[0,1] neg_hi:[0,1]
	v_pk_add_f32 v[38:39], v[38:39], v[218:219] op_sel_hi:[1,0] neg_lo:[0,1] neg_hi:[0,1]
	v_pk_add_f32 v[40:41], v[40:41], v[218:219] op_sel_hi:[1,0] neg_lo:[0,1] neg_hi:[0,1]
	v_pk_add_f32 v[42:43], v[42:43], v[218:219] op_sel_hi:[1,0] neg_lo:[0,1] neg_hi:[0,1]
	v_pk_add_f32 v[44:45], v[44:45], v[218:219] op_sel_hi:[1,0] neg_lo:[0,1] neg_hi:[0,1]
	v_pk_add_f32 v[46:47], v[46:47], v[218:219] op_sel_hi:[1,0] neg_lo:[0,1] neg_hi:[0,1]
	v_pk_add_f32 v[48:49], v[48:49], v[218:219] op_sel_hi:[1,0] neg_lo:[0,1] neg_hi:[0,1]
	v_pk_add_f32 v[50:51], v[50:51], v[218:219] op_sel_hi:[1,0] neg_lo:[0,1] neg_hi:[0,1]
	v_pk_add_f32 v[52:53], v[52:53], v[218:219] op_sel_hi:[1,0] neg_lo:[0,1] neg_hi:[0,1]
	v_pk_add_f32 v[54:55], v[54:55], v[218:219] op_sel_hi:[1,0] neg_lo:[0,1] neg_hi:[0,1]
	v_pk_add_f32 v[56:57], v[56:57], v[218:219] op_sel_hi:[1,0] neg_lo:[0,1] neg_hi:[0,1]
	v_pk_add_f32 v[58:59], v[58:59], v[218:219] op_sel_hi:[1,0] neg_lo:[0,1] neg_hi:[0,1]
	v_pk_add_f32 v[60:61], v[60:61], v[218:219] op_sel_hi:[1,0] neg_lo:[0,1] neg_hi:[0,1]
	v_pk_add_f32 v[62:63], v[62:63], v[218:219] op_sel_hi:[1,0] neg_lo:[0,1] neg_hi:[0,1]
	v_pk_add_f32 v[64:65], v[64:65], v[218:219] op_sel_hi:[1,0] neg_lo:[0,1] neg_hi:[0,1]
	v_pk_add_f32 v[66:67], v[66:67], v[218:219] op_sel_hi:[1,0] neg_lo:[0,1] neg_hi:[0,1]
	v_pk_add_f32 v[68:69], v[68:69], v[218:219] op_sel_hi:[1,0] neg_lo:[0,1] neg_hi:[0,1]
	v_pk_add_f32 v[70:71], v[70:71], v[218:219] op_sel_hi:[1,0] neg_lo:[0,1] neg_hi:[0,1]
	v_pk_add_f32 v[72:73], v[72:73], v[218:219] op_sel_hi:[1,0] neg_lo:[0,1] neg_hi:[0,1]
	v_pk_add_f32 v[74:75], v[74:75], v[218:219] op_sel_hi:[1,0] neg_lo:[0,1] neg_hi:[0,1]
	v_pk_add_f32 v[76:77], v[76:77], v[218:219] op_sel_hi:[1,0] neg_lo:[0,1] neg_hi:[0,1]
	v_pk_add_f32 v[78:79], v[78:79], v[218:219] op_sel_hi:[1,0] neg_lo:[0,1] neg_hi:[0,1]
	v_pk_add_f32 v[80:81], v[80:81], v[218:219] op_sel_hi:[1,0] neg_lo:[0,1] neg_hi:[0,1]
	v_pk_add_f32 v[82:83], v[82:83], v[218:219] op_sel_hi:[1,0] neg_lo:[0,1] neg_hi:[0,1]
	v_pk_add_f32 v[84:85], v[84:85], v[218:219] op_sel_hi:[1,0] neg_lo:[0,1] neg_hi:[0,1]
	v_pk_add_f32 v[86:87], v[86:87], v[218:219] op_sel_hi:[1,0] neg_lo:[0,1] neg_hi:[0,1]
	v_pk_add_f32 v[88:89], v[88:89], v[218:219] op_sel_hi:[1,0] neg_lo:[0,1] neg_hi:[0,1]
	v_pk_add_f32 v[90:91], v[90:91], v[218:219] op_sel_hi:[1,0] neg_lo:[0,1] neg_hi:[0,1]
	v_pk_add_f32 v[92:93], v[92:93], v[218:219] op_sel_hi:[1,0] neg_lo:[0,1] neg_hi:[0,1]
	v_exp_f32_e32 v26, v26
	v_exp_f32_e32 v27, v27
	v_exp_f32_e32 v28, v28
	v_exp_f32_e32 v29, v29
	v_exp_f32_e32 v30, v30
	v_exp_f32_e32 v31, v31
	v_exp_f32_e32 v32, v32
	v_exp_f32_e32 v33, v33
	v_exp_f32_e32 v34, v34
	v_exp_f32_e32 v35, v35
	v_exp_f32_e32 v36, v36
	v_exp_f32_e32 v37, v37
	v_exp_f32_e32 v38, v38
	v_exp_f32_e32 v39, v39
	v_exp_f32_e32 v40, v40
	v_exp_f32_e32 v41, v41
	v_exp_f32_e32 v42, v42
	v_exp_f32_e32 v43, v43
	v_exp_f32_e32 v44, v44
	v_exp_f32_e32 v45, v45
	v_exp_f32_e32 v46, v46
	v_exp_f32_e32 v47, v47
	v_exp_f32_e32 v48, v48
	v_exp_f32_e32 v49, v49
	v_exp_f32_e32 v50, v50
	v_exp_f32_e32 v51, v51
	v_exp_f32_e32 v52, v52
	v_exp_f32_e32 v53, v53
	v_exp_f32_e32 v54, v54
	v_exp_f32_e32 v55, v55
	v_exp_f32_e32 v56, v56
	v_exp_f32_e32 v57, v57
	v_exp_f32_e32 v58, v58
	v_exp_f32_e32 v59, v59
	v_exp_f32_e32 v60, v60
	v_exp_f32_e32 v61, v61
	v_exp_f32_e32 v62, v62
	v_exp_f32_e32 v63, v63
	v_exp_f32_e32 v64, v64
	v_exp_f32_e32 v65, v65
	v_exp_f32_e32 v66, v66
	v_exp_f32_e32 v67, v67
	v_exp_f32_e32 v68, v68
	v_exp_f32_e32 v69, v69
	v_exp_f32_e32 v70, v70
	v_exp_f32_e32 v71, v71
	v_exp_f32_e32 v72, v72
	v_exp_f32_e32 v73, v73
	v_exp_f32_e32 v74, v74
	v_exp_f32_e32 v75, v75
	v_exp_f32_e32 v76, v76
	v_exp_f32_e32 v77, v77
	v_exp_f32_e32 v78, v78
	v_exp_f32_e32 v79, v79
	v_exp_f32_e32 v80, v80
	v_exp_f32_e32 v81, v81
	v_exp_f32_e32 v82, v82
	v_exp_f32_e32 v83, v83
	v_exp_f32_e32 v84, v84
	v_exp_f32_e32 v85, v85
	v_exp_f32_e32 v86, v86
	v_exp_f32_e32 v87, v87
	v_exp_f32_e32 v88, v88
	v_exp_f32_e32 v89, v89
	v_exp_f32_e32 v90, v90
	v_exp_f32_e32 v91, v91
	v_exp_f32_e32 v92, v92
	v_exp_f32_e32 v93, v93
	v_pk_add_f32 v[220:221], v[26:27], v[28:29]
	v_pk_add_f32 v[220:221], v[220:221], v[30:31]
	v_pk_add_f32 v[220:221], v[220:221], v[32:33]
	v_pk_add_f32 v[220:221], v[220:221], v[34:35]
	v_pk_add_f32 v[220:221], v[220:221], v[36:37]
	v_pk_add_f32 v[220:221], v[220:221], v[38:39]
	v_pk_add_f32 v[220:221], v[220:221], v[40:41]
	v_pk_add_f32 v[220:221], v[220:221], v[42:43]
	v_pk_add_f32 v[220:221], v[220:221], v[44:45]
	v_pk_add_f32 v[220:221], v[220:221], v[46:47]
	v_pk_add_f32 v[220:221], v[220:221], v[48:49]
	v_pk_add_f32 v[220:221], v[220:221], v[50:51]
	v_pk_add_f32 v[220:221], v[220:221], v[52:53]
	v_pk_add_f32 v[220:221], v[220:221], v[54:55]
	v_pk_add_f32 v[220:221], v[220:221], v[56:57]
	v_pk_add_f32 v[220:221], v[220:221], v[58:59]
	v_pk_add_f32 v[220:221], v[220:221], v[60:61]
	v_pk_add_f32 v[220:221], v[220:221], v[62:63]
	v_pk_add_f32 v[220:221], v[220:221], v[64:65]
	v_pk_add_f32 v[220:221], v[220:221], v[66:67]
	v_pk_add_f32 v[220:221], v[220:221], v[68:69]
	v_pk_add_f32 v[220:221], v[220:221], v[70:71]
	v_pk_add_f32 v[220:221], v[220:221], v[72:73]
	v_pk_add_f32 v[220:221], v[220:221], v[74:75]
	v_pk_add_f32 v[220:221], v[220:221], v[76:77]
	v_pk_add_f32 v[220:221], v[220:221], v[78:79]
	v_pk_add_f32 v[220:221], v[220:221], v[80:81]
	v_pk_add_f32 v[220:221], v[220:221], v[82:83]
	v_pk_add_f32 v[220:221], v[220:221], v[84:85]
	v_pk_add_f32 v[220:221], v[220:221], v[86:87]
	v_pk_add_f32 v[220:221], v[220:221], v[88:89]
	v_pk_add_f32 v[220:221], v[220:221], v[90:91]
	v_pk_add_f32 v[220:221], v[220:221], v[92:93]
	v_add_f32_e32 v224, v220, v221
	ds_bpermute_b32 v225, v104, v224
	v_sub_f32_e32 v222, v106, v218
	v_cvt_pk_bf16_f32 v130, v26, v27
	v_cvt_pk_bf16_f32 v131, v28, v29
	v_cvt_pk_bf16_f32 v132, v30, v31
	v_cvt_pk_bf16_f32 v133, v32, v33
	v_cvt_pk_bf16_f32 v134, v34, v35
	v_cvt_pk_bf16_f32 v135, v36, v37
	v_cvt_pk_bf16_f32 v136, v38, v39
	v_cvt_pk_bf16_f32 v137, v40, v41
	v_cvt_pk_bf16_f32 v138, v42, v43
	v_cvt_pk_bf16_f32 v139, v44, v45
	v_cvt_pk_bf16_f32 v140, v46, v47
	v_cvt_pk_bf16_f32 v141, v48, v49
	s_waitcnt lgkmcnt(0)
; #define LAS __attribute__((address_space(3)))
; DI u32x4 pack8(const float* f) { u32x4 w; w.x = pk2(f[0], f[1]); w.y = pk2(f[2], f[3]); w.z = pk2(f[4], f[5]); w.w = pk2(f[6], f[7]); return w; }
; DI void attn_item(const Params& p, const Ctx& c, int l, int S, int tokbase, int qb, int kvh) {
;     ...
;         sum += __shfl_xor(sum, 16); sum += __shfl_xor(sum, 32);
;         sum += __builtin_amdgcn_exp2f(sink - mx);
;         f32x4 o[4];
; #pragma unroll
;         for (int dt = 0; dt < 4; ++dt) o[dt] = (f32x4){0.f, 0.f, 0.f, 0.f};
; #pragma unroll
;         for (int u = 0; u < 9; ++u) {
;             float g[8];
; #pragma unroll
;             for (int r = 0; r < 4; ++r) { g[r] = s[2 * u][r]; g[4 + r] = (2 * u + 1 < 17) ? s[(2 * u + 1 < 17) ? 2 * u + 1 : 0][r] : 0.f; }
;             const bf16x8 bfr = __builtin_bit_cast(bf16x8, pack8(g));
; #pragma unroll
;             for (int dt = 0; dt < 4; ++dt) {
;                 const LAS bf16_t* vr = VTs + (dt * 16 + lr) * VP + (kt0 + 2 * u) * 16 + lg * 4;
;                 const s16x4 lo = *(const LAS s16x4*)vr;
;                 s16x4 hi = (s16x4){0, 0, 0, 0};
;                 if (2 * u + 1 < 17) hi = *(const LAS s16x4*)(vr + 16);
;                 o[dt] = __builtin_amdgcn_mfma_f32_16x16x32_bf16(__builtin_shufflevector(lo, hi, 0, 1, 2, 3, 4, 5, 6, 7), bfr, o[dt], 0, 0, 0); }
	v_add_f32_e32 v225, v224, v225
	v_exp_f32_e32 v224, v222
	ds_bpermute_b32 v122, v105, v225
	v_cvt_pk_bf16_f32 v142, v50, v51
	v_cvt_pk_bf16_f32 v143, v52, v53
	v_cvt_pk_bf16_f32 v144, v54, v55
	v_cvt_pk_bf16_f32 v145, v56, v57
	v_cvt_pk_bf16_f32 v146, v58, v59
	v_cvt_pk_bf16_f32 v147, v60, v61
	v_cvt_pk_bf16_f32 v148, v62, v63
	v_cvt_pk_bf16_f32 v149, v64, v65
	v_cvt_pk_bf16_f32 v150, v66, v67
	v_cvt_pk_bf16_f32 v151, v68, v69
	v_cvt_pk_bf16_f32 v152, v70, v71
	v_cvt_pk_bf16_f32 v153, v72, v73
	v_cvt_pk_bf16_f32 v154, v74, v75
	v_cvt_pk_bf16_f32 v155, v76, v77
	v_cvt_pk_bf16_f32 v156, v78, v79
	v_cvt_pk_bf16_f32 v157, v80, v81
	v_cvt_pk_bf16_f32 v158, v82, v83
	v_cvt_pk_bf16_f32 v159, v84, v85
	v_cvt_pk_bf16_f32 v160, v86, v87
	v_cvt_pk_bf16_f32 v161, v88, v89
	v_cvt_pk_bf16_f32 v162, v90, v91
	v_cvt_pk_bf16_f32 v163, v92, v93
	v_mov_b32_e32 v164, 0
	v_mov_b32_e32 v165, 0
	v_add_u32_e32 v123, 0xd800, v107
	v_add_u32_e32 v124, 0x10900, v107
	v_add_u32_e32 v125, 0x13a00, v107
	v_add_u32_e32 v126, 0x16b00, v107
	v_add_u32_e32 v107, 32, v107
	ds_read2_b64 v[48:51], v123 offset1:4
	ds_read2_b64 v[52:55], v124 offset1:4
	ds_read2_b64 v[56:59], v125 offset1:4
	ds_read2_b64 v[60:63], v126 offset1:4
	ds_read2_b64 v[64:67], v123 offset0:8 offset1:12
	ds_read2_b64 v[68:71], v124 offset0:8 offset1:12
	ds_read2_b64 v[72:75], v125 offset0:8 offset1:12
	ds_read2_b64 v[76:79], v126 offset0:8 offset1:12
	ds_read2_b64 v[80:83], v123 offset0:16 offset1:20
	ds_read2_b64 v[84:87], v124 offset0:16 offset1:20
	ds_read2_b64 v[88:91], v125 offset0:16 offset1:20
	ds_read2_b64 v[92:95], v126 offset0:16 offset1:20
	s_waitcnt lgkmcnt(8)
	v_add_f32_e32 v225, v225, v122
	v_mfma_f32_16x16x32_bf16 v[42:45], v[48:51], v[130:133], 0
	v_mfma_f32_16x16x32_bf16 v[38:41], v[52:55], v[130:133], 0
	v_mfma_f32_16x16x32_bf16 v[34:37], v[56:59], v[130:133], 0
	v_mfma_f32_16x16x32_bf16 v[26:29], v[60:63], v[130:133], 0
	ds_read2_b64 v[48:51], v123 offset0:24 offset1:28
	ds_read2_b64 v[52:55], v124 offset0:24 offset1:28
	ds_read2_b64 v[56:59], v125 offset0:24 offset1:28
	ds_read2_b64 v[60:63], v126 offset0:24 offset1:28
	s_waitcnt lgkmcnt(8)
	v_mfma_f32_16x16x32_bf16 v[42:45], v[64:67], v[134:137], v[42:45]
	v_mfma_f32_16x16x32_bf16 v[38:41], v[68:71], v[134:137], v[38:41]
	v_mfma_f32_16x16x32_bf16 v[34:37], v[72:75], v[134:137], v[34:37]
	v_mfma_f32_16x16x32_bf16 v[26:29], v[76:79], v[134:137], v[26:29]
	ds_read2_b64 v[64:67], v123 offset0:32 offset1:36
	ds_read2_b64 v[68:71], v124 offset0:32 offset1:36
	ds_read2_b64 v[72:75], v125 offset0:32 offset1:36
	ds_read2_b64 v[76:79], v126 offset0:32 offset1:36
	s_waitcnt lgkmcnt(8)
	v_mfma_f32_16x16x32_bf16 v[42:45], v[80:83], v[138:141], v[42:45]
	v_mfma_f32_16x16x32_bf16 v[38:41], v[84:87], v[138:141], v[38:41]
	v_mfma_f32_16x16x32_bf16 v[34:37], v[88:91], v[138:141], v[34:37]
	v_mfma_f32_16x16x32_bf16 v[26:29], v[92:95], v[138:141], v[26:29]
	ds_read2_b64 v[80:83], v123 offset0:40 offset1:44
	ds_read2_b64 v[84:87], v124 offset0:40 offset1:44
	ds_read2_b64 v[88:91], v125 offset0:40 offset1:44
	ds_read2_b64 v[92:95], v126 offset0:40 offset1:44
	s_waitcnt lgkmcnt(8)
	v_mfma_f32_16x16x32_bf16 v[42:45], v[48:51], v[142:145], v[42:45]
	v_mfma_f32_16x16x32_bf16 v[38:41], v[52:55], v[142:145], v[38:41]
	v_mfma_f32_16x16x32_bf16 v[34:37], v[56:59], v[142:145], v[34:37]
	v_mfma_f32_16x16x32_bf16 v[26:29], v[60:63], v[142:145], v[26:29]
	ds_read2_b64 v[48:51], v123 offset0:48 offset1:52
	ds_read2_b64 v[52:55], v124 offset0:48 offset1:52
	ds_read2_b64 v[56:59], v125 offset0:48 offset1:52
	ds_read2_b64 v[60:63], v126 offset0:48 offset1:52
	s_waitcnt lgkmcnt(8)
; #define LAS __attribute__((address_space(3)))
; DI unsigned pk2(float lo, float hi) { const f2_t v = {lo, hi}; const bf2_t r = __builtin_convertvector(v, bf2_t); return __builtin_bit_cast(unsigned, r); }
; DI u32x4 pack8(const float* f) { u32x4 w; w.x = pk2(f[0], f[1]); w.y = pk2(f[2], f[3]); w.z = pk2(f[4], f[5]); w.w = pk2(f[6], f[7]); return w; }
;     DI bf16_t* fOUTS() const { return (bf16_t*)(ws + WS_OUTS); }
; DI void attn_item(const Params& p, const Ctx& c, int l, int S, int tokbase, int qb, int kvh) {
;     ...
;         for (int u = 0; u < 9; ++u) {
;             float g[8];
; #pragma unroll
;             for (int r = 0; r < 4; ++r) { g[r] = s[2 * u][r]; g[4 + r] = (2 * u + 1 < 17) ? s[(2 * u + 1 < 17) ? 2 * u + 1 : 0][r] : 0.f; }
;             const bf16x8 bfr = __builtin_bit_cast(bf16x8, pack8(g));
; #pragma unroll
;             for (int dt = 0; dt < 4; ++dt) {
;                 const LAS bf16_t* vr = VTs + (dt * 16 + lr) * VP + (kt0 + 2 * u) * 16 + lg * 4;
;                 const s16x4 lo = *(const LAS s16x4*)vr;
;                 s16x4 hi = (s16x4){0, 0, 0, 0};
;                 if (2 * u + 1 < 17) hi = *(const LAS s16x4*)(vr + 16);
;                 o[dt] = __builtin_amdgcn_mfma_f32_16x16x32_bf16(__builtin_shufflevector(lo, hi, 0, 1, 2, 3, 4, 5, 6, 7), bfr, o[dt], 0, 0, 0); }
;         }
;         const float inv = 1.f / sum;
;         bf16_t* op = c.fOUTS() + (size_t)(tokbase + qpos) * OLD + head * 64 + lg * 4;
; #pragma unroll
;         for (int dt = 0; dt < 4; ++dt) { u32x2 ov; ov.x = pk2(o[dt][0] * inv, o[dt][1] * inv); ov.y = pk2(o[dt][2] * inv, o[dt][3] * inv); *(u32x2*)(op + dt * 16) = ov; }
	v_mfma_f32_16x16x32_bf16 v[42:45], v[64:67], v[146:149], v[42:45]
	v_mfma_f32_16x16x32_bf16 v[38:41], v[68:71], v[146:149], v[38:41]
	v_mfma_f32_16x16x32_bf16 v[34:37], v[72:75], v[146:149], v[34:37]
	v_mfma_f32_16x16x32_bf16 v[26:29], v[76:79], v[146:149], v[26:29]
	ds_read2_b64 v[64:67], v123 offset0:56 offset1:60
	ds_read2_b64 v[68:71], v124 offset0:56 offset1:60
	ds_read2_b64 v[72:75], v125 offset0:56 offset1:60
	ds_read2_b64 v[76:79], v126 offset0:56 offset1:60
	s_waitcnt lgkmcnt(8)
	v_mfma_f32_16x16x32_bf16 v[42:45], v[80:83], v[150:153], v[42:45]
	v_mfma_f32_16x16x32_bf16 v[38:41], v[84:87], v[150:153], v[38:41]
	v_mfma_f32_16x16x32_bf16 v[34:37], v[88:91], v[150:153], v[34:37]
	v_mfma_f32_16x16x32_bf16 v[26:29], v[92:95], v[150:153], v[26:29]
	ds_read_b64 v[80:81], v123 offset:512
	ds_read_b64 v[84:85], v124 offset:512
	ds_read_b64 v[88:89], v125 offset:512
	ds_read_b64 v[92:93], v126 offset:512
	v_mov_b64_e32 v[82:83], 0
	v_mov_b64_e32 v[86:87], 0
	v_mov_b64_e32 v[90:91], 0
	v_mov_b64_e32 v[94:95], 0
	s_waitcnt lgkmcnt(8)
	v_mfma_f32_16x16x32_bf16 v[42:45], v[48:51], v[154:157], v[42:45]
	v_mfma_f32_16x16x32_bf16 v[38:41], v[52:55], v[154:157], v[38:41]
	v_mfma_f32_16x16x32_bf16 v[34:37], v[56:59], v[154:157], v[34:37]
	v_mfma_f32_16x16x32_bf16 v[26:29], v[60:63], v[154:157], v[26:29]
	s_waitcnt lgkmcnt(4)
	v_mfma_f32_16x16x32_bf16 v[42:45], v[64:67], v[158:161], v[42:45]
	v_mfma_f32_16x16x32_bf16 v[38:41], v[68:71], v[158:161], v[38:41]
	v_mfma_f32_16x16x32_bf16 v[34:37], v[72:75], v[158:161], v[34:37]
	v_mfma_f32_16x16x32_bf16 v[26:29], v[76:79], v[158:161], v[26:29]
	s_waitcnt lgkmcnt(0)
	v_mfma_f32_16x16x32_bf16 v[42:45], v[80:83], v[162:165], v[42:45]
	v_mfma_f32_16x16x32_bf16 v[38:41], v[84:87], v[162:165], v[38:41]
	v_mfma_f32_16x16x32_bf16 v[34:37], v[88:91], v[162:165], v[34:37]
	v_mfma_f32_16x16x32_bf16 v[26:29], v[92:95], v[162:165], v[26:29]
	v_add_f32_e32 v30, v224, v225
	v_div_scale_f32 v31, s[20:21], v30, v30, 1.0
	v_rcp_f32_e32 v32, v31
	s_nop 0
	v_fma_f32 v33, -v31, v32, 1.0
	v_fmac_f32_e32 v32, v33, v32
	v_div_scale_f32 v33, vcc, 1.0, v30, 1.0
	v_mul_f32_e32 v46, v33, v32
	v_fma_f32 v47, -v31, v46, v33
	v_fmac_f32_e32 v46, v47, v32
	v_fma_f32 v31, -v31, v46, v33
	v_div_fmas_f32 v31, v31, v32, v46
	v_div_fixup_f32 v30, v31, v30, 1.0
	v_add_u32_e32 v31, s40, v1
	v_pk_mul_f32 v[42:43], v[30:31], v[42:43] op_sel_hi:[0,1]
	v_pk_mul_f32 v[44:45], v[30:31], v[44:45] op_sel_hi:[0,1]
	v_pk_mul_f32 v[38:39], v[30:31], v[38:39] op_sel_hi:[0,1]
	v_pk_mul_f32 v[40:41], v[30:31], v[40:41] op_sel_hi:[0,1]
	v_pk_mul_f32 v[34:35], v[30:31], v[34:35] op_sel_hi:[0,1]
	v_pk_mul_f32 v[36:37], v[30:31], v[36:37] op_sel_hi:[0,1]
	v_pk_mul_f32 v[26:27], v[30:31], v[26:27] op_sel_hi:[0,1]
	v_pk_mul_f32 v[28:29], v[30:31], v[28:29] op_sel_hi:[0,1]
	v_mad_i64_i32 v[32:33], s[20:21], v31, s22, v[98:99]
	v_cvt_pk_bf16_f32 v42, v42, v43
	v_cvt_pk_bf16_f32 v43, v44, v45
	v_cvt_pk_bf16_f32 v38, v38, v39
	v_cvt_pk_bf16_f32 v39, v40, v41
	v_cvt_pk_bf16_f32 v34, v34, v35
	v_cvt_pk_bf16_f32 v35, v36, v37
	v_cvt_pk_bf16_f32 v26, v26, v27
	v_cvt_pk_bf16_f32 v27, v28, v29
	global_store_dwordx2 v[32:33], v[42:43], off
	global_store_dwordx2 v[32:33], v[38:39], off offset:32
	global_store_dwordx2 v[32:33], v[34:35], off offset:64
	global_store_dwordx2 v[32:33], v[26:27], off offset:96
	s_mov_b64 s[20:21], 0x18000
	s_add_i32 s40, s40, 16
	v_mov_b64_e32 v[32:33], v[24:25]
	v_mov_b64_e32 v[28:29], v[20:21]
	v_lshl_add_u64 v[100:101], v[100:101], 0, s[20:21]
	s_cmp_lg_u32 s40, 64
	v_mov_b64_e32 v[30:31], v[22:23]
	v_mov_b64_e32 v[26:27], v[18:19]
	s_cbranch_scc0 .LBB0_323

; #define LAS __attribute__((address_space(3)))
; DI u32x4 pack8(const float* f) { u32x4 w; w.x = pk2(f[0], f[1]); w.y = pk2(f[2], f[3]); w.z = pk2(f[4], f[5]); w.w = pk2(f[6], f[7]); return w; }
;     DI float* fROPE() const { return (float*)(ws + WS_ROPE); }
; DI void attn_item(const Params& p, const Ctx& c, int l, int S, int tokbase, int qb, int kvh) {
;     ...
;     for (int j = 0; j < 4; ++j) {
;         const int qi = qh * 64 + 16 * j + lr, qpos = qb * 128 + qi, kt0 = qh * 4 + j;
;         float f0[8], f1[8]; unpack8(nq0, f0); unpack8(nq1, f1);
;         if (j < 3) { nq0 = *(const u32x4*)(qbase + (size_t)(16 * (j + 1)) * P1LD); nq1 = *(const u32x4*)(qbase + (size_t)(16 * (j + 1)) * P1LD + 32); }
;         float ss = 0.f;
; #pragma unroll
;         for (int i = 0; i < 8; ++i) ss += f0[i] * f0[i] + f1[i] * f1[i];
;         ss += __shfl_xor(ss, 16); ss += __shfl_xor(ss, 32);
;         const float rstd = rsqrtf(ss * (1.f / 64.f) + EPS);
; #pragma unroll
;         for (int i = 0; i < 8; ++i) { f0[i] *= rstd * g0[i]; f1[i] *= rstd * g1[i]; }
;         const float* rr = c.fROPE() + qpos * 16;
; #pragma unroll
;         for (int i = 0; i < 8; ++i) { const float other = __shfl_xor(f0[i], 16), cs = rr[i], sn = rr[8 + i];
;             if (lg == 0) f0[i] = f0[i] * cs - other * sn; else if (lg == 1) f0[i] = f0[i] * cs + other * sn; }
; #pragma unroll
;         for (int i = 0; i < 8; ++i) { f0[i] *= 0.18033688011112042f; f1[i] *= 0.18033688011112042f; }
;         const bf16x8 qf0 = __builtin_bit_cast(bf16x8, pack8(f0)), qf1 = __builtin_bit_cast(bf16x8, pack8(f1));
;         f32x4 s[17];
;         float mx = sink;
; #pragma unroll
;         for (int t = 0; t < 17; ++t) {
;             s[t] = (f32x4){0.f, 0.f, 0.f, 0.f};
;             const LAS bf16_t* kr = Ks + ((kt0 + t) * 16 + lr) * KP + lg * 8;
;             s[t] = __builtin_amdgcn_mfma_f32_16x16x32_bf16(*(const LAS bf16x8*)kr, qf0, s[t], 0, 0, 0);
;             s[t] = __builtin_amdgcn_mfma_f32_16x16x32_bf16(*(const LAS bf16x8*)(kr + 32), qf1, s[t], 0, 0, 0);
.LBB0_319:
	v_lshlrev_b32_e32 v56, 16, v26
	v_and_b32_e32 v57, 0xffff0000, v26
	v_lshlrev_b32_e32 v34, 16, v30
	v_and_b32_e32 v35, 0xffff0000, v30
	v_lshlrev_b32_e32 v52, 16, v27
	v_and_b32_e32 v53, 0xffff0000, v27
	v_pk_mul_f32 v[26:27], v[56:57], v[56:57]
	v_lshlrev_b32_e32 v54, 16, v31
	v_and_b32_e32 v55, 0xffff0000, v31
	v_lshlrev_b32_e32 v48, 16, v28
	v_and_b32_e32 v49, 0xffff0000, v28
	v_lshlrev_b32_e32 v42, 16, v29
	v_and_b32_e32 v43, 0xffff0000, v29
	v_pk_fma_f32 v[26:27], v[34:35], v[34:35], v[26:27]
	v_pk_mul_f32 v[28:29], v[52:53], v[52:53]
	v_add_f32_e32 v26, v26, v27
	v_pk_fma_f32 v[28:29], v[54:55], v[54:55], v[28:29]
	v_lshlrev_b32_e32 v50, 16, v32
	v_and_b32_e32 v51, 0xffff0000, v32
	v_pk_mul_f32 v[30:31], v[48:49], v[48:49]
	v_add_f32_e32 v26, v28, v26
	v_pk_fma_f32 v[30:31], v[50:51], v[50:51], v[30:31]
	v_add_f32_e32 v26, v29, v26
	v_lshlrev_b32_e32 v44, 16, v33
	v_and_b32_e32 v45, 0xffff0000, v33
	v_pk_mul_f32 v[32:33], v[42:43], v[42:43]
	v_add_f32_e32 v26, v30, v26
	v_pk_fma_f32 v[32:33], v[44:45], v[44:45], v[32:33]
	v_add_f32_e32 v26, v31, v26
	v_add_f32_e32 v26, v32, v26
	v_add_f32_e32 v26, v33, v26
	ds_bpermute_b32 v27, v104, v26
	v_readlane_b32 s20, v254, 25
	v_ashrrev_i32_e32 v103, 31, v102
	v_readlane_b32 s21, v254, 26
	s_mov_b64 s[38:39], -1
	s_waitcnt lgkmcnt(0)
	v_add_f32_e32 v26, v26, v27
	ds_bpermute_b32 v27, v105, v26
	v_lshl_add_u64 v[38:39], v[102:103], 2, s[20:21]
	v_add_u32_e32 v103, 0, v108
	s_waitcnt lgkmcnt(0)
	v_add_f32_e32 v26, v26, v27
	v_fmamk_f32 v26, v26, 0x3c800000, v205
	v_cmp_gt_f32_e32 vcc, s79, v26
	v_mul_f32_e32 v27, 0x4b800000, v26
	s_nop 0
	v_cndmask_b32_e32 v26, v26, v27, vcc
	v_rsq_f32_e32 v26, v26
	s_nop 0
	v_mul_f32_e32 v27, 0x45800000, v26
	v_cndmask_b32_e32 v46, v26, v27, vcc
	v_pk_mul_f32 v[26:27], v[6:7], v[46:47] op_sel_hi:[1,0]
	s_andn2_b64 vcc, exec, s[36:37]
	v_pk_mul_f32 v[58:59], v[26:27], v[34:35]
	global_load_dwordx4 v[26:29], v[38:39], off offset:48
	global_load_dwordx4 v[34:37], v[38:39], off offset:32
	global_load_dwordx4 v[30:33], v[38:39], off offset:16
	s_nop 0
	global_load_dwordx4 v[38:41], v[38:39], off
	ds_bpermute_b32 v60, v104, v58
	ds_bpermute_b32 v61, v104, v59
	ds_read_b128 v[66:69], v103 offset:20800
	ds_read_b128 v[70:73], v103 offset:23104
	ds_read_b128 v[74:77], v103 offset:25408
	ds_read_b128 v[78:81], v103 offset:27712
	ds_read_b128 v[82:85], v103 offset:30016
	ds_read_b128 v[86:89], v103 offset:32320
	ds_read_b128 v[110:113], v103 offset:34624
	s_waitcnt vmcnt(0)
	v_pk_mul_f32 v[38:39], v[38:39], v[58:59]
	s_waitcnt lgkmcnt(7)
	v_pk_fma_f32 v[62:63], v[34:35], v[60:61], v[38:39] neg_lo:[1,0,0] neg_hi:[1,0,0]
	v_pk_fma_f32 v[34:35], v[34:35], v[60:61], v[38:39]
	v_pk_mul_f32 v[38:39], v[14:15], v[46:47] op_sel_hi:[1,0]
	v_cndmask_b32_e64 v34, v58, v34, s[44:45]
	v_pk_mul_f32 v[38:39], v[38:39], v[56:57]
	v_pk_mul_f32 v[56:57], v[8:9], v[46:47] op_sel_hi:[1,0]
	v_cndmask_b32_e64 v35, v59, v35, s[44:45]
	v_pk_mul_f32 v[54:55], v[56:57], v[54:55]
	ds_bpermute_b32 v56, v104, v54
	ds_bpermute_b32 v57, v104, v55
	v_cndmask_b32_e64 v35, v35, v63, s[42:43]
	v_cndmask_b32_e64 v34, v34, v62, s[42:43]
	v_pk_mul_f32 v[34:35], v[34:35], s[78:79] op_sel_hi:[1,0]
	v_pk_mul_f32 v[38:39], v[38:39], s[78:79] op_sel_hi:[1,0]
	s_waitcnt lgkmcnt(0)
	v_pk_mul_f32 v[36:37], v[36:37], v[56:57]
	v_cvt_pk_bf16_f32 v94, v34, v35
	v_pk_fma_f32 v[56:57], v[40:41], v[54:55], v[36:37] neg_lo:[0,0,1] neg_hi:[0,0,1]
	v_pk_fma_f32 v[36:37], v[40:41], v[54:55], v[36:37]
	v_pk_mul_f32 v[40:41], v[16:17], v[46:47] op_sel_hi:[1,0]
	v_cndmask_b32_e64 v36, v54, v36, s[44:45]
	v_pk_mul_f32 v[40:41], v[40:41], v[52:53]
	v_pk_mul_f32 v[52:53], v[2:3], v[46:47] op_sel_hi:[1,0]
	v_cndmask_b32_e64 v37, v55, v37, s[44:45]
	v_pk_mul_f32 v[50:51], v[52:53], v[50:51]
	ds_bpermute_b32 v52, v104, v50
	ds_bpermute_b32 v53, v104, v51
	v_cndmask_b32_e64 v37, v37, v57, s[42:43]
	v_cndmask_b32_e64 v36, v36, v56, s[42:43]
	v_pk_mul_f32 v[36:37], v[36:37], s[78:79] op_sel_hi:[1,0]
	v_pk_mul_f32 v[40:41], v[40:41], s[78:79] op_sel_hi:[1,0]
	s_waitcnt lgkmcnt(0)
	v_pk_mul_f32 v[26:27], v[26:27], v[52:53]
	v_cvt_pk_bf16_f32 v95, v36, v37
	v_pk_fma_f32 v[52:53], v[50:51], v[30:31], v[26:27] neg_lo:[0,0,1] neg_hi:[0,0,1]
	v_pk_fma_f32 v[26:27], v[50:51], v[30:31], v[26:27]
	v_pk_mul_f32 v[30:31], v[10:11], v[46:47] op_sel_hi:[1,0]
	v_cndmask_b32_e64 v26, v50, v26, s[44:45]
	v_pk_mul_f32 v[30:31], v[30:31], v[48:49]
	v_pk_mul_f32 v[48:49], v[4:5], v[46:47] op_sel_hi:[1,0]
	v_cndmask_b32_e64 v27, v51, v27, s[44:45]
	v_pk_mul_f32 v[44:45], v[48:49], v[44:45]
	ds_bpermute_b32 v48, v104, v44
	ds_bpermute_b32 v49, v104, v45
	v_cndmask_b32_e64 v27, v27, v53, s[42:43]
	v_cndmask_b32_e64 v26, v26, v52, s[42:43]
	v_pk_mul_f32 v[26:27], v[26:27], s[78:79] op_sel_hi:[1,0]
	v_pk_mul_f32 v[30:31], v[30:31], s[78:79] op_sel_hi:[1,0]
	s_waitcnt lgkmcnt(0)
	v_pk_mul_f32 v[28:29], v[28:29], v[48:49]
	v_cvt_pk_bf16_f32 v96, v26, v27
	v_pk_fma_f32 v[48:49], v[44:45], v[32:33], v[28:29] neg_lo:[0,0,1] neg_hi:[0,0,1]
	v_pk_fma_f32 v[28:29], v[44:45], v[32:33], v[28:29]
	v_pk_mul_f32 v[32:33], v[12:13], v[46:47] op_sel_hi:[1,0]
	v_cndmask_b32_e64 v28, v44, v28, s[44:45]
	v_cndmask_b32_e64 v29, v45, v29, s[44:45]
	v_cndmask_b32_e64 v29, v29, v49, s[42:43]
	v_cndmask_b32_e64 v28, v28, v48, s[42:43]
	v_pk_mul_f32 v[28:29], v[28:29], s[78:79] op_sel_hi:[1,0]
	v_pk_mul_f32 v[32:33], v[32:33], v[42:43]
	v_cvt_pk_bf16_f32 v97, v28, v29
	ds_read_b128 v[26:29], v103
	v_pk_mul_f32 v[32:33], v[32:33], s[78:79] op_sel_hi:[1,0]
	v_cvt_pk_bf16_f32 v92, v30, v31
	v_cvt_pk_bf16_f32 v93, v32, v33
	ds_read_b128 v[30:33], v103 offset:64
	s_waitcnt lgkmcnt(1)
; #define LAS __attribute__((address_space(3)))
; DI void attn_item(const Params& p, const Ctx& c, int l, int S, int tokbase, int qb, int kvh) {
;     ...
;         f32x4 s[17];
;         float mx = sink;
; #pragma unroll
;         for (int t = 0; t < 17; ++t) {
;             s[t] = (f32x4){0.f, 0.f, 0.f, 0.f};
;             const LAS bf16_t* kr = Ks + ((kt0 + t) * 16 + lr) * KP + lg * 8;
;             s[t] = __builtin_amdgcn_mfma_f32_16x16x32_bf16(*(const LAS bf16x8*)kr, qf0, s[t], 0, 0, 0);
;             s[t] = __builtin_amdgcn_mfma_f32_16x16x32_bf16(*(const LAS bf16x8*)(kr + 32), qf1, s[t], 0, 0, 0);
;         }
;         if (interior) {
; #pragma unroll
;             for (int t = 0; t < 17; ++t)
; #pragma unroll
;                 for (int r = 0; r < 4; ++r) {
;                     if (t == 0 && !(lg * 4 + r >= lr)) s[t][r] = -INFINITY;
;                     if (t == 16 && !(lg * 4 + r <= lr)) s[t][r] = -INFINITY;
;                     mx = fmaxf(mx, s[t][r]); }
;         } else {
; #pragma unroll
;             for (int t = 0; t < 17; ++t)
; #pragma unroll
;                 for (int r = 0; r < 4; ++r) { const int kpos = kstart + (kt0 + t) * 16 + lg * 4 + r;
;                     bool valid = (kpos >= 0) && (kpos < S);
;                     if (t == 0) valid = valid && (lg * 4 + r >= lr);
;                     if (t == 16) valid = valid && (lg * 4 + r <= lr);
;                     const float v = valid ? s[t][r] : -INFINITY; s[t][r] = v; mx = fmaxf(mx, v); }
	v_mfma_f32_16x16x32_bf16 v[26:29], v[26:29], v[94:97], 0
	v_cvt_pk_bf16_f32 v90, v38, v39
	v_cvt_pk_bf16_f32 v91, v40, v41
	ds_read_b128 v[34:37], v103 offset:2368
	ds_read_b128 v[38:41], v103 offset:4672
	s_waitcnt lgkmcnt(2)
	v_mfma_f32_16x16x32_bf16 v[26:29], v[30:33], v[90:93], v[26:29]
	ds_read_b128 v[30:33], v103 offset:2304
	ds_read_b128 v[42:45], v103 offset:6976
	ds_read_b128 v[46:49], v103 offset:9280
	s_waitcnt lgkmcnt(2)
	v_mfma_f32_16x16x32_bf16 v[30:33], v[30:33], v[94:97], 0
	ds_read_b128 v[50:53], v103 offset:11584
	ds_read_b128 v[54:57], v103 offset:13888
	ds_read_b128 v[58:61], v103 offset:16192
	v_mfma_f32_16x16x32_bf16 v[30:33], v[34:37], v[90:93], v[30:33]
	ds_read_b128 v[34:37], v103 offset:4608
	ds_read_b128 v[62:65], v103 offset:18496
	s_waitcnt lgkmcnt(1)
	v_mfma_f32_16x16x32_bf16 v[34:37], v[34:37], v[94:97], 0
	v_mfma_f32_16x16x32_bf16 v[34:37], v[38:41], v[90:93], v[34:37]
	ds_read_b128 v[38:41], v103 offset:6912
	s_waitcnt lgkmcnt(0)
	v_mfma_f32_16x16x32_bf16 v[38:41], v[38:41], v[94:97], 0
	v_mfma_f32_16x16x32_bf16 v[38:41], v[42:45], v[90:93], v[38:41]
	ds_read_b128 v[42:45], v103 offset:9216
	s_waitcnt lgkmcnt(0)
	v_mfma_f32_16x16x32_bf16 v[42:45], v[42:45], v[94:97], 0
	v_mfma_f32_16x16x32_bf16 v[42:45], v[46:49], v[90:93], v[42:45]
	ds_read_b128 v[46:49], v103 offset:11520
	s_waitcnt lgkmcnt(0)
	v_mfma_f32_16x16x32_bf16 v[46:49], v[46:49], v[94:97], 0
	v_mfma_f32_16x16x32_bf16 v[46:49], v[50:53], v[90:93], v[46:49]
	ds_read_b128 v[50:53], v103 offset:13824
	s_waitcnt lgkmcnt(0)
	v_mfma_f32_16x16x32_bf16 v[50:53], v[50:53], v[94:97], 0
	v_mfma_f32_16x16x32_bf16 v[50:53], v[54:57], v[90:93], v[50:53]
	ds_read_b128 v[54:57], v103 offset:16128
	s_waitcnt lgkmcnt(0)
	v_mfma_f32_16x16x32_bf16 v[54:57], v[54:57], v[94:97], 0
	v_mfma_f32_16x16x32_bf16 v[54:57], v[58:61], v[90:93], v[54:57]
	ds_read_b128 v[58:61], v103 offset:18432
	s_waitcnt lgkmcnt(0)
	v_mfma_f32_16x16x32_bf16 v[58:61], v[58:61], v[94:97], 0
	v_mfma_f32_16x16x32_bf16 v[58:61], v[62:65], v[90:93], v[58:61]
	ds_read_b128 v[62:65], v103 offset:20736
	s_waitcnt lgkmcnt(0)
	v_mfma_f32_16x16x32_bf16 v[62:65], v[62:65], v[94:97], 0
	v_mfma_f32_16x16x32_bf16 v[62:65], v[66:69], v[90:93], v[62:65]
	ds_read_b128 v[66:69], v103 offset:23040
	s_waitcnt lgkmcnt(0)
	v_mfma_f32_16x16x32_bf16 v[66:69], v[66:69], v[94:97], 0
	v_mfma_f32_16x16x32_bf16 v[66:69], v[70:73], v[90:93], v[66:69]
	ds_read_b128 v[70:73], v103 offset:25344
	s_waitcnt lgkmcnt(0)
	v_mfma_f32_16x16x32_bf16 v[70:73], v[70:73], v[94:97], 0
	v_mfma_f32_16x16x32_bf16 v[70:73], v[74:77], v[90:93], v[70:73]
	ds_read_b128 v[74:77], v103 offset:27648
	s_waitcnt lgkmcnt(0)
	v_mfma_f32_16x16x32_bf16 v[74:77], v[74:77], v[94:97], 0
	v_mfma_f32_16x16x32_bf16 v[74:77], v[78:81], v[90:93], v[74:77]
	ds_read_b128 v[78:81], v103 offset:29952
	s_waitcnt lgkmcnt(0)
	v_mfma_f32_16x16x32_bf16 v[78:81], v[78:81], v[94:97], 0
	v_mfma_f32_16x16x32_bf16 v[78:81], v[82:85], v[90:93], v[78:81]
	ds_read_b128 v[82:85], v103 offset:32256
	s_waitcnt lgkmcnt(0)
	v_mfma_f32_16x16x32_bf16 v[82:85], v[82:85], v[94:97], 0
	v_mfma_f32_16x16x32_bf16 v[82:85], v[86:89], v[90:93], v[82:85]
	ds_read_b128 v[86:89], v103 offset:34560
	s_waitcnt lgkmcnt(0)
	v_mfma_f32_16x16x32_bf16 v[86:89], v[86:89], v[94:97], 0
	v_mfma_f32_16x16x32_bf16 v[86:89], v[110:113], v[90:93], v[86:89]
	ds_read_b128 v[110:113], v103 offset:36864
	s_waitcnt lgkmcnt(0)
	v_mfma_f32_16x16x32_bf16 v[94:97], v[110:113], v[94:97], 0
	ds_read_b128 v[110:113], v103 offset:36928
	s_waitcnt lgkmcnt(0)
	v_mfma_f32_16x16x32_bf16 v[90:93], v[110:113], v[90:93], v[94:97]
	s_cbranch_vccnz .LBB0_321
	s_add_i32 s2, s41, s40
	s_add_i32 s20, s2, 0xffffff80
	v_add_u32_e32 v144, s40, v109
	v_add_u32_e32 v94, 0xffffff80, v144
	s_cmp_gt_i32 s20, -1
	s_cselect_b64 s[20:21], -1, 0
	v_cmp_gt_i32_e32 vcc, s30, v94
	s_and_b64 s[24:25], s[20:21], vcc
	s_and_b64 vcc, s[24:25], s[46:47]
	v_add_u32_e32 v94, 0xffffff81, v144
	v_cndmask_b32_e32 v26, v208, v26, vcc
	v_cmp_gt_i32_e32 vcc, s30, v94
	s_and_b64 s[24:25], s[20:21], vcc
	s_and_b64 vcc, s[24:25], s[48:49]
	v_add_u32_e32 v95, 0xffffff82, v144
	v_cndmask_b32_e32 v27, v208, v27, vcc
	v_cmp_gt_i32_e32 vcc, s30, v95
	s_and_b64 s[24:25], s[20:21], vcc
	s_and_b64 vcc, s[24:25], s[50:51]
	v_add_u32_e32 v95, 0xffffff83, v144
	v_cndmask_b32_e32 v28, v208, v28, vcc
	v_cmp_gt_i32_e32 vcc, s30, v95
	s_and_b64 s[20:21], s[20:21], vcc
	s_and_b64 vcc, s[20:21], s[52:53]
	s_add_i32 s20, s2, 0xffffff90
	v_add_u32_e32 v95, 0xffffff90, v144
	s_cmp_gt_i32 s20, -1
	v_cndmask_b32_e32 v29, v208, v29, vcc
	s_cselect_b64 s[20:21], -1, 0
	v_cmp_gt_i32_e32 vcc, s30, v95
	s_and_b64 vcc, s[20:21], vcc
	v_add_u32_e32 v95, 0xffffff91, v144
	v_cndmask_b32_e32 v30, v208, v30, vcc
	v_cmp_gt_i32_e32 vcc, s30, v95
	s_and_b64 vcc, s[20:21], vcc
	v_add_u32_e32 v95, 0xffffff92, v144
	v_cndmask_b32_e32 v31, v208, v31, vcc
	v_cmp_gt_i32_e32 vcc, s30, v95
	s_and_b64 vcc, s[20:21], vcc
	v_add_u32_e32 v95, 0xffffff93, v144
	v_cndmask_b32_e32 v32, v208, v32, vcc
	v_cmp_gt_i32_e32 vcc, s30, v95
	s_and_b64 vcc, s[20:21], vcc
	s_add_i32 s20, s2, 0xffffffa0
	v_add_u32_e32 v95, 0xffffffa0, v144
	s_cmp_gt_i32 s20, -1
	v_cndmask_b32_e32 v33, v208, v33, vcc
	s_cselect_b64 s[20:21], -1, 0
	v_cmp_gt_i32_e32 vcc, s30, v95
	s_and_b64 vcc, s[20:21], vcc
	v_add_u32_e32 v95, 0xffffffa1, v144
	v_cndmask_b32_e32 v34, v208, v34, vcc
	v_cmp_gt_i32_e32 vcc, s30, v95
	s_and_b64 vcc, s[20:21], vcc
	v_add_u32_e32 v95, 0xffffffa2, v144
	v_cndmask_b32_e32 v35, v208, v35, vcc
	v_cmp_gt_i32_e32 vcc, s30, v95
	s_and_b64 vcc, s[20:21], vcc
	v_add_u32_e32 v95, 0xffffffa3, v144
	v_cndmask_b32_e32 v36, v208, v36, vcc
; DI void attn_item(const Params& p, const Ctx& c, int l, int S, int tokbase, int qb, int kvh) {
;     ...
; #pragma unroll
;             for (int t = 0; t < 17; ++t)
; #pragma unroll
;                 for (int r = 0; r < 4; ++r) { const int kpos = kstart + (kt0 + t) * 16 + lg * 4 + r;
;                     bool valid = (kpos >= 0) && (kpos < S);
;                     if (t == 0) valid = valid && (lg * 4 + r >= lr);
;                     if (t == 16) valid = valid && (lg * 4 + r <= lr);
;                     const float v = valid ? s[t][r] : -INFINITY; s[t][r] = v; mx = fmaxf(mx, v); }
;         }
	v_cmp_gt_i32_e32 vcc, s30, v95
	s_and_b64 vcc, s[20:21], vcc
	s_add_i32 s20, s2, 0xffffffb0
	v_add_u32_e32 v95, 0xffffffb0, v144
	s_cmp_gt_i32 s20, -1
	v_cndmask_b32_e32 v37, v208, v37, vcc
	s_cselect_b64 s[20:21], -1, 0
	v_cmp_gt_i32_e32 vcc, s30, v95
	s_and_b64 vcc, s[20:21], vcc
	v_add_u32_e32 v95, 0xffffffb1, v144
	v_cndmask_b32_e32 v38, v208, v38, vcc
	v_cmp_gt_i32_e32 vcc, s30, v95
	s_and_b64 vcc, s[20:21], vcc
	v_add_u32_e32 v95, 0xffffffb2, v144
	v_cndmask_b32_e32 v39, v208, v39, vcc
	v_cmp_gt_i32_e32 vcc, s30, v95
	s_and_b64 vcc, s[20:21], vcc
	v_add_u32_e32 v95, 0xffffffb3, v144
	v_cndmask_b32_e32 v40, v208, v40, vcc
	v_cmp_gt_i32_e32 vcc, s30, v95
	s_and_b64 vcc, s[20:21], vcc
	s_sub_i32 s20, s2, 64
	v_subrev_u32_e32 v95, 64, v144
	s_cmp_gt_i32 s20, -1
	v_cndmask_b32_e32 v41, v208, v41, vcc
	s_cselect_b64 s[20:21], -1, 0
	v_cmp_gt_i32_e32 vcc, s30, v95
	s_and_b64 vcc, s[20:21], vcc
	v_subrev_u32_e32 v95, 63, v144
	v_cndmask_b32_e32 v42, v208, v42, vcc
	v_cmp_gt_i32_e32 vcc, s30, v95
	s_and_b64 vcc, s[20:21], vcc
	v_subrev_u32_e32 v95, 62, v144
	v_cndmask_b32_e32 v43, v208, v43, vcc
	v_cmp_gt_i32_e32 vcc, s30, v95
	s_and_b64 vcc, s[20:21], vcc
	v_subrev_u32_e32 v95, 61, v144
	v_cndmask_b32_e32 v44, v208, v44, vcc
	v_cmp_gt_i32_e32 vcc, s30, v95
	s_and_b64 vcc, s[20:21], vcc
	s_sub_i32 s20, s2, 48
	v_subrev_u32_e32 v95, 48, v144
	s_cmp_gt_i32 s20, -1
	v_cndmask_b32_e32 v45, v208, v45, vcc
	s_cselect_b64 s[20:21], -1, 0
	v_cmp_gt_i32_e32 vcc, s30, v95
	s_and_b64 vcc, s[20:21], vcc
	v_subrev_u32_e32 v95, 47, v144
	v_cndmask_b32_e32 v46, v208, v46, vcc
	v_cmp_gt_i32_e32 vcc, s30, v95
	s_and_b64 vcc, s[20:21], vcc
	v_subrev_u32_e32 v95, 46, v144
	v_cndmask_b32_e32 v47, v208, v47, vcc
	v_cmp_gt_i32_e32 vcc, s30, v95
	s_and_b64 vcc, s[20:21], vcc
	v_subrev_u32_e32 v95, 45, v144
	v_cndmask_b32_e32 v48, v208, v48, vcc
	v_cmp_gt_i32_e32 vcc, s30, v95
	s_and_b64 vcc, s[20:21], vcc
	s_sub_i32 s20, s2, 32
	v_subrev_u32_e32 v95, 32, v144
	s_cmp_gt_i32 s20, -1
	v_cndmask_b32_e32 v49, v208, v49, vcc
	s_cselect_b64 s[20:21], -1, 0
	v_cmp_gt_i32_e32 vcc, s30, v95
	s_and_b64 vcc, s[20:21], vcc
	v_subrev_u32_e32 v95, 31, v144
	v_cndmask_b32_e32 v50, v208, v50, vcc
	v_cmp_gt_i32_e32 vcc, s30, v95
	s_and_b64 vcc, s[20:21], vcc
	v_subrev_u32_e32 v95, 30, v144
	v_cndmask_b32_e32 v51, v208, v51, vcc
	v_cmp_gt_i32_e32 vcc, s30, v95
	s_and_b64 vcc, s[20:21], vcc
	v_subrev_u32_e32 v95, 29, v144
	v_cndmask_b32_e32 v52, v208, v52, vcc
	v_cmp_gt_i32_e32 vcc, s30, v95
	s_and_b64 vcc, s[20:21], vcc
	s_add_i32 s20, s2, -16
	v_add_u32_e32 v95, -16, v144
	s_cmp_gt_i32 s20, -1
	v_cndmask_b32_e32 v53, v208, v53, vcc
	s_cselect_b64 s[20:21], -1, 0
	v_cmp_gt_i32_e32 vcc, s30, v95
	s_and_b64 vcc, s[20:21], vcc
	v_add_u32_e32 v95, -15, v144
	v_cndmask_b32_e32 v54, v208, v54, vcc
	v_cmp_gt_i32_e32 vcc, s30, v95
	s_and_b64 vcc, s[20:21], vcc
	v_add_u32_e32 v95, -14, v144
	v_cndmask_b32_e32 v55, v208, v55, vcc
	v_cmp_gt_i32_e32 vcc, s30, v95
	s_and_b64 vcc, s[20:21], vcc
	v_add_u32_e32 v95, -13, v144
	v_cndmask_b32_e32 v56, v208, v56, vcc
	v_cmp_gt_i32_e32 vcc, s30, v95
	s_and_b64 vcc, s[20:21], vcc
	s_cmp_gt_i32 s2, -1
	v_cndmask_b32_e32 v57, v208, v57, vcc
	s_cselect_b64 s[20:21], -1, 0
	v_cmp_gt_i32_e32 vcc, s30, v144
	s_and_b64 vcc, s[20:21], vcc
	v_add_u32_e32 v95, 1, v144
	v_cndmask_b32_e32 v58, v208, v58, vcc
	v_cmp_gt_i32_e32 vcc, s30, v95
	s_and_b64 vcc, s[20:21], vcc
	v_add_u32_e32 v95, 2, v144
	v_cndmask_b32_e32 v59, v208, v59, vcc
	v_cmp_gt_i32_e32 vcc, s30, v95
	s_and_b64 vcc, s[20:21], vcc
	v_add_u32_e32 v95, 3, v144
	v_cndmask_b32_e32 v60, v208, v60, vcc
	v_cmp_gt_i32_e32 vcc, s30, v95
	s_and_b64 vcc, s[20:21], vcc
	s_add_i32 s20, s2, 16
	v_add_u32_e32 v95, 16, v144
	s_cmp_gt_i32 s20, -1
	v_cndmask_b32_e32 v61, v208, v61, vcc
	s_cselect_b64 s[20:21], -1, 0
	v_cmp_gt_i32_e32 vcc, s30, v95
	s_and_b64 vcc, s[20:21], vcc
	v_add_u32_e32 v95, 17, v144
	v_cndmask_b32_e32 v62, v208, v62, vcc
	v_cmp_gt_i32_e32 vcc, s30, v95
	s_and_b64 vcc, s[20:21], vcc
	v_add_u32_e32 v95, 18, v144
	v_cndmask_b32_e32 v63, v208, v63, vcc
	v_cmp_gt_i32_e32 vcc, s30, v95
	s_and_b64 vcc, s[20:21], vcc
	v_add_u32_e32 v95, 19, v144
	v_cndmask_b32_e32 v64, v208, v64, vcc
	v_cmp_gt_i32_e32 vcc, s30, v95
	s_and_b64 vcc, s[20:21], vcc
	s_add_i32 s20, s2, 32
	v_add_u32_e32 v95, 32, v144
	s_cmp_gt_i32 s20, -1
	v_cndmask_b32_e32 v65, v208, v65, vcc
	s_cselect_b64 s[20:21], -1, 0
	v_cmp_gt_i32_e32 vcc, s30, v95
	s_and_b64 vcc, s[20:21], vcc
	v_add_u32_e32 v95, 33, v144
	v_cndmask_b32_e32 v66, v208, v66, vcc
	v_cmp_gt_i32_e32 vcc, s30, v95
	s_and_b64 vcc, s[20:21], vcc
	v_add_u32_e32 v95, 34, v144
	v_cndmask_b32_e32 v67, v208, v67, vcc
	v_cmp_gt_i32_e32 vcc, s30, v95
	s_and_b64 vcc, s[20:21], vcc
	v_add_u32_e32 v95, 35, v144
	v_cndmask_b32_e32 v68, v208, v68, vcc
	v_cmp_gt_i32_e32 vcc, s30, v95
	s_and_b64 vcc, s[20:21], vcc
	s_add_i32 s20, s2, 48
	v_add_u32_e32 v95, 48, v144
	s_cmp_gt_i32 s20, -1
	v_max3_f32 v94, v106, v26, v27
	v_cndmask_b32_e32 v69, v208, v69, vcc
	s_cselect_b64 s[20:21], -1, 0
	v_cmp_gt_i32_e32 vcc, s30, v95
	v_max3_f32 v94, v94, v28, v29
	s_and_b64 vcc, s[20:21], vcc
	v_add_u32_e32 v95, 49, v144
	v_max3_f32 v94, v94, v30, v31
	v_cndmask_b32_e32 v70, v208, v70, vcc
	v_cmp_gt_i32_e32 vcc, s30, v95
	v_max3_f32 v94, v94, v32, v33
	s_and_b64 vcc, s[20:21], vcc
	v_add_u32_e32 v95, 50, v144
	v_max3_f32 v94, v94, v34, v35
	v_cndmask_b32_e32 v71, v208, v71, vcc
	v_cmp_gt_i32_e32 vcc, s30, v95
	v_max3_f32 v94, v94, v36, v37
	s_and_b64 vcc, s[20:21], vcc
	v_add_u32_e32 v95, 51, v144
	v_max3_f32 v94, v94, v38, v39
	v_cndmask_b32_e32 v72, v208, v72, vcc
	v_cmp_gt_i32_e32 vcc, s30, v95
; DI void attn_item(const Params& p, const Ctx& c, int l, int S, int tokbase, int qb, int kvh) {
;     ...
;         if (interior) {
; #pragma unroll
;             for (int t = 0; t < 17; ++t)
; #pragma unroll
;                 for (int r = 0; r < 4; ++r) {
;                     if (t == 0 && !(lg * 4 + r >= lr)) s[t][r] = -INFINITY;
;                     if (t == 16 && !(lg * 4 + r <= lr)) s[t][r] = -INFINITY;
;                     mx = fmaxf(mx, s[t][r]); }
;         } else {
; #pragma unroll
;             for (int t = 0; t < 17; ++t)
; #pragma unroll
;                 for (int r = 0; r < 4; ++r) { const int kpos = kstart + (kt0 + t) * 16 + lg * 4 + r;
;                     bool valid = (kpos >= 0) && (kpos < S);
;                     if (t == 0) valid = valid && (lg * 4 + r >= lr);
;                     if (t == 16) valid = valid && (lg * 4 + r <= lr);
;                     const float v = valid ? s[t][r] : -INFINITY; s[t][r] = v; mx = fmaxf(mx, v); }
;         }
	v_max3_f32 v94, v94, v40, v41
	s_and_b64 vcc, s[20:21], vcc
	s_add_i32 s20, s2, 64
	v_max3_f32 v94, v94, v42, v43
	v_add_u32_e32 v95, 64, v144
	s_cmp_gt_i32 s20, -1
	v_max3_f32 v94, v94, v44, v45
	v_cndmask_b32_e32 v73, v208, v73, vcc
	s_cselect_b64 s[20:21], -1, 0
	v_cmp_gt_i32_e32 vcc, s30, v95
	v_max3_f32 v94, v94, v46, v47
	s_and_b64 vcc, s[20:21], vcc
	v_add_u32_e32 v95, 0x41, v144
	v_max3_f32 v94, v94, v48, v49
	v_cndmask_b32_e32 v74, v208, v74, vcc
	v_cmp_gt_i32_e32 vcc, s30, v95
	v_max3_f32 v94, v94, v50, v51
	s_and_b64 vcc, s[20:21], vcc
	v_add_u32_e32 v95, 0x42, v144
	v_max3_f32 v94, v94, v52, v53
	v_cndmask_b32_e32 v75, v208, v75, vcc
	v_cmp_gt_i32_e32 vcc, s30, v95
	v_max3_f32 v94, v94, v54, v55
	s_and_b64 vcc, s[20:21], vcc
	v_add_u32_e32 v95, 0x43, v144
	v_max3_f32 v94, v94, v56, v57
	v_cndmask_b32_e32 v76, v208, v76, vcc
	v_cmp_gt_i32_e32 vcc, s30, v95
	v_max3_f32 v94, v94, v58, v59
	s_and_b64 vcc, s[20:21], vcc
	s_add_i32 s20, s2, 0x50
	v_max3_f32 v94, v94, v60, v61
	v_add_u32_e32 v95, 0x50, v144
	s_cmp_gt_i32 s20, -1
	v_max3_f32 v94, v94, v62, v63
	v_cndmask_b32_e32 v77, v208, v77, vcc
	s_cselect_b64 s[20:21], -1, 0
	v_cmp_gt_i32_e32 vcc, s30, v95
	v_max3_f32 v94, v94, v64, v65
	s_and_b64 vcc, s[20:21], vcc
	v_add_u32_e32 v95, 0x51, v144
	v_max3_f32 v94, v94, v66, v67
	v_cndmask_b32_e32 v78, v208, v78, vcc
	v_cmp_gt_i32_e32 vcc, s30, v95
	v_max3_f32 v94, v94, v68, v69
	s_and_b64 vcc, s[20:21], vcc
	v_add_u32_e32 v95, 0x52, v144
	v_max3_f32 v94, v94, v70, v71
	v_cndmask_b32_e32 v79, v208, v79, vcc
	v_cmp_gt_i32_e32 vcc, s30, v95
	v_max3_f32 v94, v94, v72, v73
	s_and_b64 vcc, s[20:21], vcc
	v_add_u32_e32 v95, 0x53, v144
	v_max3_f32 v94, v94, v74, v75
	v_cndmask_b32_e32 v80, v208, v80, vcc
	v_cmp_gt_i32_e32 vcc, s30, v95
	v_max3_f32 v94, v94, v76, v77
	s_and_b64 vcc, s[20:21], vcc
	v_max3_f32 v94, v94, v78, v79
	v_cndmask_b32_e32 v81, v208, v81, vcc
	s_add_i32 s20, s2, 0x60
	v_max3_f32 v95, v94, v80, v81
	v_add_u32_e32 v94, 0x60, v144
	s_cmp_gt_i32 s20, -1
	s_cselect_b64 s[20:21], -1, 0
	v_cmp_gt_i32_e32 vcc, s30, v94
	s_and_b64 vcc, s[20:21], vcc
	v_add_u32_e32 v110, 0x61, v144
	v_cndmask_b32_e32 v82, v208, v82, vcc
	v_cmp_gt_i32_e32 vcc, s30, v110
	s_and_b64 vcc, s[20:21], vcc
	v_add_u32_e32 v110, 0x62, v144
	v_cndmask_b32_e32 v83, v208, v83, vcc
	v_cmp_gt_i32_e32 vcc, s30, v110
	s_and_b64 vcc, s[20:21], vcc
	v_add_u32_e32 v110, 0x63, v144
	v_cndmask_b32_e32 v84, v208, v84, vcc
	v_cmp_gt_i32_e32 vcc, s30, v110
	s_and_b64 vcc, s[20:21], vcc
	v_max3_f32 v95, v95, v82, v83
	v_cndmask_b32_e32 v85, v208, v85, vcc
	s_add_i32 s20, s2, 0x70
	v_max3_f32 v110, v95, v84, v85
	v_add_u32_e32 v95, 0x70, v144
	s_cmp_gt_i32 s20, -1
	s_cselect_b64 s[20:21], -1, 0
	v_cmp_gt_i32_e32 vcc, s30, v95
	s_and_b64 vcc, s[20:21], vcc
	v_add_u32_e32 v111, 0x71, v144
	v_cndmask_b32_e32 v86, v208, v86, vcc
	v_cmp_gt_i32_e32 vcc, s30, v111
	s_and_b64 vcc, s[20:21], vcc
	v_add_u32_e32 v111, 0x72, v144
	v_cndmask_b32_e32 v87, v208, v87, vcc
	v_cmp_gt_i32_e32 vcc, s30, v111
	s_and_b64 vcc, s[20:21], vcc
	v_add_u32_e32 v111, 0x73, v144
	v_cndmask_b32_e32 v88, v208, v88, vcc
	v_cmp_gt_i32_e32 vcc, s30, v111
	s_and_b64 vcc, s[20:21], vcc
	v_max3_f32 v110, v110, v86, v87
	v_cndmask_b32_e32 v89, v208, v89, vcc
	s_addk_i32 s2, 0x80
	v_max3_f32 v121, v110, v88, v89
	v_add_u32_e32 v110, 0x80, v144
	s_cmp_gt_i32 s2, -1
	s_cselect_b64 s[20:21], -1, 0
	v_cmp_gt_i32_e32 vcc, s30, v110
	s_and_b64 s[24:25], s[20:21], vcc
	s_and_b64 vcc, s[24:25], s[54:55]
	v_add_u32_e32 v111, 0x81, v144
	v_cndmask_b32_e32 v90, v208, v90, vcc
	v_cmp_gt_i32_e32 vcc, s30, v111
	s_and_b64 s[24:25], s[20:21], vcc
	s_and_b64 vcc, s[24:25], s[56:57]
	v_cndmask_b32_e32 v91, v208, v91, vcc
	v_max3_f32 v174, v121, v90, v91
	v_add_u32_e32 v121, 0x82, v144
	v_cmp_gt_i32_e32 vcc, s30, v121
	s_and_b64 s[24:25], s[20:21], vcc
	s_and_b64 vcc, s[24:25], s[58:59]
	v_add_u32_e32 v144, 0x83, v144
	v_cndmask_b32_e32 v92, v208, v92, vcc
	v_cmp_gt_i32_e32 vcc, s30, v144
	s_and_b64 s[20:21], s[20:21], vcc
	s_and_b64 vcc, s[20:21], s[60:61]
	v_cndmask_b32_e32 v93, v208, v93, vcc
	v_max3_f32 v188, v174, v92, v93
	s_mov_b64 s[38:39], 0
.LBB0_321:
	s_andn2_b64 vcc, exec, s[38:39]
	s_cbranch_vccnz .LBB0_316
	s_mov_b32 s2, 0xff800000
	v_mov_b32_e32 v216, s2
	v_cndmask_b32_e64 v26, v26, v216, s[56:57]
	v_cndmask_b32_e64 v27, v27, v208, s[62:63]
	v_max3_f32 v217, v106, v26, v27
	v_cndmask_b32_e64 v28, v28, v208, s[64:65]
	v_cndmask_b32_e64 v29, v29, v208, s[66:67]
	v_max3_f32 v217, v217, v28, v29
	v_max3_f32 v217, v217, v30, v31
	v_max3_f32 v217, v217, v32, v33
	v_max3_f32 v217, v217, v34, v35
	v_max3_f32 v217, v217, v36, v37
	v_max3_f32 v217, v217, v38, v39
	v_max3_f32 v217, v217, v40, v41
	v_max3_f32 v217, v217, v42, v43
	v_max3_f32 v217, v217, v44, v45
	v_max3_f32 v217, v217, v46, v47
	v_max3_f32 v217, v217, v48, v49
	v_max3_f32 v217, v217, v50, v51
	v_max3_f32 v217, v217, v52, v53
	v_max3_f32 v217, v217, v54, v55
	v_max3_f32 v217, v217, v56, v57
	v_max3_f32 v217, v217, v58, v59
	v_max3_f32 v217, v217, v60, v61
	v_max3_f32 v217, v217, v62, v63
	v_max3_f32 v217, v217, v64, v65
	v_max3_f32 v217, v217, v66, v67
	v_max3_f32 v217, v217, v68, v69
	v_max3_f32 v217, v217, v70, v71
	v_max3_f32 v217, v217, v72, v73
	v_max3_f32 v217, v217, v74, v75
	v_max3_f32 v217, v217, v76, v77
	v_max3_f32 v217, v217, v78, v79
	v_max3_f32 v217, v217, v80, v81
	v_max3_f32 v217, v217, v82, v83
	v_max3_f32 v217, v217, v84, v85
	v_max3_f32 v217, v217, v86, v87
	v_max3_f32 v217, v217, v88, v89
	v_cndmask_b32_e64 v218, v90, v216, s[68:69]
	v_cndmask_b32_e64 v91, v208, v91, s[56:57]
	v_cndmask_b32_e64 v90, v218, v90, s[56:57]
	v_max3_f32 v217, v217, v218, v91
	v_cndmask_b32_e64 v92, v92, v208, s[70:71]
	v_cndmask_b32_e64 v93, v93, v208, s[72:73]
	v_max3_f32 v188, v217, v92, v93
	s_branch .LBB0_316
